# parked waves touch the leading weight K-tiles of the next phase during the w_o/up/down seams
# baseline (speedup 1.0000x reference)
.Lxb4_end:
.LBB0_776:
	s_or_b64 exec, exec, s[0:1]
	v_readlane_b32 s88, v252, 6
	v_readlane_b32 s89, v252, 7
	s_lshr_b32 s90, s72, 6
	s_mul_i32 s90, s90, 0x80000
	s_add_u32 s88, s88, 0xf20000
	s_addc_u32 s89, s89, 0
	s_add_u32 s88, s88, s90
	s_addc_u32 s89, s89, 0
	v_lshrrev_b32_e32 v253, 1, v176
	v_and_b32_e32 v254, 1, v176
	v_lshlrev_b32_e32 v253, 11, v253
	v_lshl_or_b32 v253, v254, 7, v253
	global_load_dword v254, v253, s[88:89]
	v_readlane_b32 s8, v252, 0
	v_readlane_b32 s9, v252, 1
	v_readlane_b32 s10, v252, 2
	v_readlane_b32 s11, v252, 3
	v_readlane_b32 s12, v252, 4
	v_readlane_b32 s13, v252, 5
	v_readlane_b32 s14, v252, 6
	v_readlane_b32 s15, v252, 7
	s_mov_b64 s[8:9], s[12:13]
	s_mov_b64 s[10:11], s[14:15]
	s_add_u32 s3, s10, 0xb240000
	v_mov_b32_e32 v178, v176
	s_waitcnt lgkmcnt(0)
	s_barrier
	s_addc_u32 s38, s11, 0
	s_and_b64 vcc, exec, s[4:5]
	v_readfirstlane_b32 s11, v178
	s_cbranch_vccnz .LBB0_869
	s_ashr_i32 s39, s72, 31
	s_lshr_b32 s0, s39, 29
	s_add_i32 s2, s72, s0
	s_and_b32 s0, s2, -8
	s_sub_i32 s7, s72, s0
	s_cmp_gt_i32 s7, -1
	s_cbranch_scc0 .LBB0_779
	s_lshl_b32 s6, s7, 5
	s_cbranch_execz .LBB0_780
	s_branch .LBB0_781

.Lxb5_end:
.LBB0_1060:
	s_mov_b32 s100, 0
	s_or_b64 exec, exec, s[0:1]
	v_readlane_b32 s88, v252, 6
	v_readlane_b32 s89, v252, 7
	s_lshr_b32 s90, s72, 6
	s_mul_i32 s90, s90, 0x80000
	s_add_u32 s88, s88, 0x1120000
	s_addc_u32 s89, s89, 0
	s_add_u32 s88, s88, s90
	s_addc_u32 s89, s89, 0
	v_lshrrev_b32_e32 v253, 1, v176
	v_and_b32_e32 v254, 1, v176
	v_lshlrev_b32_e32 v253, 11, v253
	v_lshl_or_b32 v253, v254, 7, v253
	global_load_dword v254, v253, s[88:89]
	v_readlane_b32 s8, v252, 0
	v_readlane_b32 s9, v252, 1
	v_readlane_b32 s10, v252, 2
	v_readlane_b32 s11, v252, 3
	v_readlane_b32 s12, v252, 4
	v_readlane_b32 s13, v252, 5
	v_readlane_b32 s14, v252, 6
	v_readlane_b32 s15, v252, 7
	s_mov_b64 s[8:9], s[12:13]
	s_mov_b64 s[10:11], s[14:15]
	s_add_u32 s8, s10, 0x4160000
	s_addc_u32 s9, s11, 0
	v_mov_b32_e32 v9, v176
	s_waitcnt lgkmcnt(0)
	s_barrier
	s_cmpk_gt_i32 s72, 0x3ff
	v_readfirstlane_b32 s7, v9
	s_cbranch_scc1 .LBB0_1086
	s_ashr_i32 s2, s72, 31
	s_lshr_b32 s0, s2, 29
	s_add_i32 s3, s72, s0
	s_and_b32 s0, s3, -8
	s_sub_i32 s10, s72, s0
	s_cmp_gt_i32 s10, -1
	s_cbranch_scc0 .LBB0_1063
	s_lshl_b32 s6, s10, 7
	s_cbranch_execz .LBB0_1064
	s_branch .LBB0_1065

.Lxb6_end:
.LBB0_1143:
	s_or_b64 exec, exec, s[0:1]
	v_readlane_b32 s88, v252, 6
	v_readlane_b32 s89, v252, 7
	s_lshr_b32 s90, s72, 6
	s_mul_i32 s90, s90, 0x200000
	s_add_u32 s88, s88, 0x1920000
	s_addc_u32 s89, s89, 0
	s_add_u32 s88, s88, s90
	s_addc_u32 s89, s89, 0
	v_lshrrev_b32_e32 v253, 1, v176
	v_and_b32_e32 v254, 1, v176
	v_lshlrev_b32_e32 v253, 13, v253
	v_lshl_or_b32 v253, v254, 7, v253
	global_load_dword v254, v253, s[88:89]
	v_mov_b32_e32 v148, v176
	s_waitcnt lgkmcnt(0)
	s_barrier
	s_and_b64 vcc, exec, s[4:5]
	v_readfirstlane_b32 s33, v148
	s_cbranch_vccnz .LBB0_1218
	s_ashr_i32 s36, s72, 31
	s_lshr_b32 s0, s36, 29
	s_add_i32 s7, s72, s0
	s_and_b32 s0, s7, -8
	s_sub_i32 s6, s72, s0
	s_cmp_gt_i32 s6, -1
	s_cbranch_scc0 .LBB0_1146
	s_lshl_b32 s2, s6, 5
	s_ashr_i32 s0, s7, 3
	s_cbranch_execz .LBB0_1147
	s_branch .LBB0_1148

	.amdhsa_kernel _Z14fwd_megakernel3Ctx
		.amdhsa_group_segment_fixed_size 0
		.amdhsa_private_segment_fixed_size 0
		.amdhsa_kernarg_size 416
		.amdhsa_user_sgpr_count 2
		.amdhsa_user_sgpr_dispatch_ptr 0
		.amdhsa_user_sgpr_queue_ptr 0
		.amdhsa_user_sgpr_kernarg_segment_ptr 1
		.amdhsa_user_sgpr_dispatch_id 0
		.amdhsa_user_sgpr_kernarg_preload_length 0
		.amdhsa_user_sgpr_kernarg_preload_offset 0
		.amdhsa_user_sgpr_private_segment_size 0
		.amdhsa_uses_dynamic_stack 0
		.amdhsa_enable_private_segment 0
		.amdhsa_system_sgpr_workgroup_id_x 1
		.amdhsa_system_sgpr_workgroup_id_y 0
		.amdhsa_system_sgpr_workgroup_id_z 0
		.amdhsa_system_sgpr_workgroup_info 0
		.amdhsa_system_vgpr_workitem_id 2
		.amdhsa_next_free_vgpr 255
		.amdhsa_next_free_sgpr 102
		.amdhsa_accum_offset 256
		.amdhsa_reserve_vcc 1
		.amdhsa_float_round_mode_32 0
		.amdhsa_float_round_mode_16_64 0
		.amdhsa_float_denorm_mode_32 3
		.amdhsa_float_denorm_mode_16_64 3
		.amdhsa_dx10_clamp 1
		.amdhsa_ieee_mode 1
		.amdhsa_fp16_overflow 0
		.amdhsa_tg_split 0
		.amdhsa_exception_fp_ieee_invalid_op 0
		.amdhsa_exception_fp_denorm_src 0
		.amdhsa_exception_fp_ieee_div_zero 0
		.amdhsa_exception_fp_ieee_overflow 0
		.amdhsa_exception_fp_ieee_underflow 0
		.amdhsa_exception_fp_ieee_inexact 0
		.amdhsa_exception_int_div_zero 0
	.end_amdhsa_kernel

amdhsa.kernels:
  - .agpr_count:     0
    .args:
      - .offset:         0
        .size:           160
        .value_kind:     by_value
      - .offset:         160
        .size:           4
        .value_kind:     hidden_block_count_x
      - .offset:         164
        .size:           4
        .value_kind:     hidden_block_count_y
      - .offset:         168
        .size:           4
        .value_kind:     hidden_block_count_z
      - .offset:         172
        .size:           2
        .value_kind:     hidden_group_size_x
      - .offset:         174
        .size:           2
        .value_kind:     hidden_group_size_y
      - .offset:         176
        .size:           2
        .value_kind:     hidden_group_size_z
      - .offset:         178
        .size:           2
        .value_kind:     hidden_remainder_x
      - .offset:         180
        .size:           2
        .value_kind:     hidden_remainder_y
      - .offset:         182
        .size:           2
        .value_kind:     hidden_remainder_z
      - .offset:         200
        .size:           8
        .value_kind:     hidden_global_offset_x
      - .offset:         208
        .size:           8
        .value_kind:     hidden_global_offset_y
      - .offset:         216
        .size:           8
        .value_kind:     hidden_global_offset_z
      - .offset:         224
        .size:           2
        .value_kind:     hidden_grid_dims
      - .offset:         248
        .size:           8
        .value_kind:     hidden_multigrid_sync_arg
      - .offset:         280
        .size:           4
        .value_kind:     hidden_dynamic_lds_size
    .group_segment_fixed_size: 0
    .kernarg_segment_align: 8
    .kernarg_segment_size: 416
    .language:       OpenCL C
    .language_version:
      - 2
      - 0
    .max_flat_workgroup_size: 512
    .name:           _Z14fwd_megakernel3Ctx
    .private_segment_fixed_size: 0
    .sgpr_count:     108
    .sgpr_spill_count: 59
    .symbol:         _Z14fwd_megakernel3Ctx.kd
    .uniform_work_group_size: 1
    .uses_dynamic_stack: false
    .vgpr_count:     255
    .vgpr_spill_count: 0
    .wavefront_size: 64
